# v8: + coarser lgkm waits (one per MFMA pair), saddr-form K/V prefetch loads, fewer canonicalising max ops
# speedup vs baseline: 1.0024x; 1.0024x over previous
.LBB0_525:
	s_mul_i32 s7, s7, 0x9800
	s_mul_hi_u32 s8, s6, 0x9800
	s_and_b32 s4, s10, 15
	s_add_i32 s8, s8, s7
	s_mul_i32 s6, s6, 0x9800
	s_add_u32 s6, s50, s6
	s_addc_u32 s7, s51, s8
	s_lshl_b32 s4, s4, 8
	s_add_u32 s48, s6, s4
	s_addc_u32 s49, s7, 0
	s_lshl_b32 s4, s11, 2
	s_bfe_u32 s6, s10, 0x20002
	s_or_b32 s26, s4, s6
	v_mbcnt_lo_u32_b32 v76, -1, 0
	v_mbcnt_hi_u32_b32 v76, -1, v76
	s_mul_i32 s6, s26, 0x210000
	v_add_u32_e32 v54, s39, v76
	v_ashrrev_i32_e32 v16, 4, v54
	s_mul_hi_i32 s4, s26, 0x210000
	s_add_u32 s40, s52, s6
	v_lshlrev_b32_e32 v22, 3, v76
	v_add_u32_e32 v18, 32, v16
	s_addc_u32 s41, s53, s4
	v_and_b32_e32 v0, 0x78, v22
	v_ashrrev_i32_e32 v17, 31, v16
	v_ashrrev_i32_e32 v19, 31, v18
	s_add_u32 s42, s54, s6
	v_lshlrev_b32_e32 v23, 1, v0
	v_lshlrev_b64 v[48:49], 8, v[16:17]
	v_lshlrev_b64 v[8:9], 8, v[18:19]
	s_addc_u32 s43, s55, s4
	v_or_b32_e32 v52, v48, v23
	v_mov_b32_e32 v53, v49
	v_or_b32_e32 v8, v8, v23
	v_lshl_add_u64 v[0:1], s[42:43], 0, v[52:53]
	v_lshl_add_u64 v[4:5], s[42:43], 0, v[8:9]
	v_lshl_add_u64 v[10:11], s[40:41], 0, v[52:53]
	v_lshl_add_u64 v[12:13], s[40:41], 0, v[8:9]
	global_load_dwordx4 v[0:3], v[0:1], off
	s_nop 0
	global_load_dwordx4 v[4:7], v[4:5], off
	s_nop 0
	global_load_dwordx4 v[8:11], v[10:11], off
	s_nop 0
	global_load_dwordx4 v[12:15], v[12:13], off
	v_ashrrev_i32_e32 v55, 1, v54
	s_movk_i32 s4, 0xffe0
	v_bfe_u32 v97, v76, 5, 1
	v_bfi_b32 v17, s4, v55, v76
	v_mov_b64_e32 v[20:21], s[48:49]
	v_mad_i64_i32 v[20:21], s[6:7], v17, s21, v[20:21]
	v_lshlrev_b32_e32 v50, 4, v97
	v_mov_b32_e32 v51, v96
	v_lshl_add_u64 v[20:21], v[20:21], 0, v[50:51]
	global_load_dwordx4 v[118:121], v[20:21], off
	global_load_dwordx4 v[114:117], v[20:21], off offset:32
	global_load_dwordx4 v[126:129], v[20:21], off offset:64
	global_load_dwordx4 v[122:125], v[20:21], off offset:96
	global_load_dwordx4 v[110:113], v[20:21], off offset:128
	global_load_dwordx4 v[106:109], v[20:21], off offset:160
	global_load_dwordx4 v[102:105], v[20:21], off offset:192
	global_load_dwordx4 v[98:101], v[20:21], off offset:224
	v_bfe_u32 v17, v22, 5, 2
	v_and_b32_e32 v22, 0xfffff0, v16
	v_lshlrev_b32_e32 v24, 1, v16
	v_lshrrev_b32_e32 v25, 1, v16
	v_and_b32_e32 v26, 3, v16
	v_and_b32_e32 v19, 0xf0, v54
	v_lshlrev_b32_e32 v16, 8, v16
	v_and_or_b32 v22, v24, 8, v22
	v_and_or_b32 v24, v25, 4, v26
	v_and_b32_e32 v26, 0xfffff0, v18
	v_lshlrev_b32_e32 v27, 1, v18
	v_bitop3_b32 v16, v23, v16, v19 bitop3:0xde
	v_lshlrev_b32_e32 v18, 8, v18
	v_lshrrev_b32_e32 v22, 1, v22
	v_and_or_b32 v26, v27, 8, v26
	v_add_u32_e32 v188, 0, v16
	v_bitop3_b32 v16, v18, v23, v19 bitop3:0xf6
	v_or_b32_e32 v18, v22, v17
	v_lshrrev_b32_e32 v19, 1, v26
	v_and_b32_e32 v25, 48, v23
	v_lshlrev_b32_e32 v24, 6, v24
	v_add_u32_e32 v189, 0, v16
	v_lshlrev_b32_e32 v16, 9, v18
	v_or_b32_e32 v17, v19, v17
	v_or3_b32 v16, v16, v24, v25
	v_lshlrev_b32_e32 v17, 9, v17
	v_and_b32_e32 v180, 31, v76
	v_lshlrev_b32_e32 v51, 4, v76
	v_or3_b32 v17, v17, v24, v25
	v_add_u32_e32 v190, 0, v16
	v_add_u32_e32 v191, 0, v17
	s_waitcnt vmcnt(0)
	s_add_i32 s4, 0, 0x10000
	s_mov_b64 s[6:7], 0x6000
	v_and_b32_e32 v181, 0xffffffe0, v55
	v_and_b32_e32 v77, 63, v76
	s_mov_b32 s8, s5
	s_mov_b32 s9, s5
	s_mov_b32 s10, s5
	s_mov_b32 s11, s5
	s_mov_b32 s12, s5
	s_waitcnt vmcnt(0)
	ds_write_b128 v190, v[0:3]
	s_waitcnt vmcnt(10)
	ds_write_b128 v191, v[4:7]
	s_waitcnt vmcnt(9)
	ds_write_b128 v188, v[8:11] offset:32768
	s_waitcnt vmcnt(8)
	ds_write_b128 v189, v[12:15] offset:32768
	v_lshlrev_b32_e32 v12, 8, v180
	v_and_b32_e32 v13, 0xf0, v51
	v_bitop3_b32 v0, v50, v12, v13 bitop3:0xde
	v_add_u32_e32 v192, 0, v0
	s_waitcnt lgkmcnt(0)
	s_barrier
	ds_read_b128 v[0:3], v192 offset:32768
	ds_read_b128 v[4:7], v192 offset:40960
	s_waitcnt vmcnt(7) lgkmcnt(1)
	v_mfma_f32_32x32x16_bf16 v[16:31], v[0:3], v[118:121], 0
	v_or_b32_e32 v0, 32, v50
	v_bitop3_b32 v0, v0, v12, v13 bitop3:0xde
	v_add_u32_e32 v200, 0, v0
	v_lshl_add_u64 v[8:9], v[52:53], 0, s[6:7]
	v_lshl_add_u64 v[10:11], s[42:43], 0, v[8:9]
	v_lshlrev_b32_e32 v14, 3, v77
	v_and_b32_e32 v15, 0xc0, v51
	s_waitcnt lgkmcnt(0)
	v_mfma_f32_32x32x16_bf16 v[32:47], v[4:7], v[118:121], 0
	ds_read_b128 v[0:3], v200 offset:32768
	ds_read_b128 v[4:7], v200 offset:40960
	s_mov_b32 s6, s5
	s_mov_b32 s7, s5
	s_mov_b32 s13, s5
	s_mov_b32 s14, s5
	s_mov_b32 s15, s5
	s_mov_b32 s16, s5
	s_waitcnt vmcnt(6) lgkmcnt(1)
	v_mfma_f32_32x32x16_bf16 v[16:31], v[0:3], v[114:117], v[16:31]
	v_or_b32_e32 v0, 64, v50
	v_bitop3_b32 v0, v0, v12, v13 bitop3:0xde
	v_add_u32_e32 v199, 0, v0
	s_mov_b32 s17, s5
	s_mov_b32 s18, s5
	s_mov_b32 s19, s5
	s_cmp_lg_u32 0, -1
	s_waitcnt lgkmcnt(0)
	v_mfma_f32_32x32x16_bf16 v[32:47], v[4:7], v[114:117], v[32:47]
	ds_read_b128 v[0:3], v199 offset:32768
	ds_read_b128 v[4:7], v199 offset:40960
	s_cselect_b32 s27, 0, 0
	v_lshlrev_b32_e32 v183, 2, v97
	v_mov_b32_e32 v185, 0
	s_waitcnt vmcnt(5) lgkmcnt(1)
	v_mfma_f32_32x32x16_bf16 v[16:31], v[0:3], v[126:129], v[16:31]
	v_or_b32_e32 v0, 0x60, v50
	v_bitop3_b32 v0, v0, v12, v13 bitop3:0xde
	v_add_u32_e32 v198, 0, v0
	s_waitcnt lgkmcnt(0)
	v_mfma_f32_32x32x16_bf16 v[32:47], v[4:7], v[126:129], v[32:47]
	ds_read_b128 v[0:3], v198 offset:32768
	ds_read_b128 v[4:7], v198 offset:40960
	s_waitcnt vmcnt(4) lgkmcnt(1)
	v_mfma_f32_32x32x16_bf16 v[16:31], v[0:3], v[122:125], v[16:31]
	v_or_b32_e32 v0, 0x80, v50
	v_bitop3_b32 v0, v0, v12, v13 bitop3:0xde
	v_add_u32_e32 v195, 0, v0
	s_waitcnt lgkmcnt(0)
	v_mfma_f32_32x32x16_bf16 v[32:47], v[4:7], v[122:125], v[32:47]
	ds_read_b128 v[0:3], v195 offset:32768
	ds_read_b128 v[4:7], v195 offset:40960
	s_waitcnt vmcnt(3) lgkmcnt(1)
	v_mfma_f32_32x32x16_bf16 v[16:31], v[0:3], v[110:113], v[16:31]
	v_or_b32_e32 v0, 0xa0, v50
	v_bitop3_b32 v0, v0, v12, v13 bitop3:0xde
	v_add_u32_e32 v193, 0, v0
	ds_read_b128 v[0:3], v193 offset:32768
	s_waitcnt lgkmcnt(1)
	v_mfma_f32_32x32x16_bf16 v[32:47], v[4:7], v[110:113], v[32:47]
	v_and_b32_e32 v4, 0x3fffffc0, v54
	v_lshl_add_u32 v78, v4, 2, s4
	ds_read_b128 v[4:7], v193 offset:40960
	s_mov_b32 s4, s5
	v_add_u32_e32 v182, v78, v50
	v_lshl_add_u32 v184, v180, 2, v78
	s_waitcnt vmcnt(2) lgkmcnt(1)
	v_mfma_f32_32x32x16_bf16 v[16:31], v[0:3], v[106:109], v[16:31]
	v_lshl_add_u64 v[0:1], v[52:53], 0, s[68:69]
	v_lshl_add_u64 v[2:3], s[42:43], 0, v[0:1]
	v_lshl_add_u64 v[0:1], s[40:41], 0, v[0:1]
	global_load_dwordx4 v[54:57], v[2:3], off
	global_load_dwordx4 v[58:61], v[10:11], off
	v_lshl_add_u64 v[2:3], s[40:41], 0, v[8:9]
	global_load_dwordx4 v[62:65], v[0:1], off
	global_load_dwordx4 v[66:69], v[2:3], off
	v_or_b32_e32 v0, 0xc0, v50
	v_bitop3_b32 v0, v0, v12, v13 bitop3:0xde
	v_add_u32_e32 v202, 0, v0
	ds_read_b128 v[0:3], v202 offset:32768
	v_lshlrev_b32_e32 v9, 1, v76
	v_and_or_b32 v8, v14, 24, v15
	s_waitcnt lgkmcnt(1)
	v_mfma_f32_32x32x16_bf16 v[32:47], v[4:7], v[106:109], v[32:47]
	v_and_b32_e32 v4, 32, v9
	v_and_b32_e32 v5, 0x100, v14
	v_or3_b32 v51, v8, v4, v5
	ds_read_b128 v[4:7], v202 offset:40960
	v_add_u32_e32 v187, s27, v51
	s_waitcnt vmcnt(5) lgkmcnt(1)
	v_mfma_f32_32x32x16_bf16 v[16:31], v[0:3], v[102:105], v[16:31]
	v_or_b32_e32 v0, 0xe0, v50
	v_bitop3_b32 v0, v0, v12, v13 bitop3:0xde
	v_add_u32_e32 v201, 0, v0
	ds_read_b128 v[0:3], v201 offset:32768
	ds_read_b128 v[70:73], v201 offset:40960
	s_waitcnt lgkmcnt(2)
	v_mfma_f32_32x32x16_bf16 v[32:47], v[4:7], v[102:105], v[32:47]
	s_waitcnt vmcnt(4) lgkmcnt(1)
	v_mfma_f32_32x32x16_bf16 v[16:31], v[0:3], v[98:101], v[16:31]
	v_mov_b64_e32 v[0:1], s[4:5]
	v_mov_b64_e32 v[2:3], s[6:7]
	v_mov_b64_e32 v[4:5], s[8:9]
	v_mov_b64_e32 v[6:7], s[10:11]
	v_mov_b64_e32 v[8:9], s[12:13]
	v_mov_b64_e32 v[10:11], s[14:15]
	v_mov_b64_e32 v[12:13], s[16:17]
	s_waitcnt lgkmcnt(0)
	v_mfma_f32_32x32x16_bf16 v[32:47], v[70:73], v[98:101], v[32:47]
	s_nop 2
	v_max_f32_e32 v70, v17, v17
	v_max_f32_e32 v71, v16, v16
	v_max_f32_e32 v70, v71, v70
	v_max3_f32 v70, v70, v18, v19
	v_max3_f32 v70, v70, v20, v21
	v_max3_f32 v70, v70, v22, v23
	v_max3_f32 v70, v70, v24, v25
	v_max3_f32 v70, v70, v26, v27
	v_max3_f32 v70, v70, v28, v29
	v_max3_f32 v70, v70, v30, v31
	v_max3_f32 v70, v70, v32, v33
	v_max3_f32 v70, v70, v34, v35
	v_max3_f32 v70, v70, v36, v37
	v_max3_f32 v70, v70, v38, v39
	v_max3_f32 v70, v70, v40, v41
	v_max3_f32 v70, v70, v42, v43
	v_mov_b64_e32 v[14:15], s[18:19]
	v_max3_f32 v70, v70, v44, v45
	s_mov_b64 s[6:7], 0x8000
	v_max3_f32 v79, v70, v46, v47
	v_lshl_add_u64 v[70:71], v[52:53], 0, s[6:7]
	s_mov_b64 s[6:7], 0xa000
	v_lshl_add_u64 v[72:73], s[42:43], 0, v[70:71]
	v_lshl_add_u64 v[52:53], v[52:53], 0, s[6:7]
	v_lshl_add_u64 v[70:71], s[40:41], 0, v[70:71]
	v_lshl_add_u64 v[74:75], s[42:43], 0, v[52:53]
	global_load_dwordx4 v[130:133], v[72:73], off
	global_load_dwordx4 v[138:141], v[74:75], off
	v_lshl_add_u64 v[52:53], s[40:41], 0, v[52:53]
	global_load_dwordx4 v[134:137], v[70:71], off
	global_load_dwordx4 v[142:145], v[52:53], off
	v_mov_b32_e32 v80, v79
	s_nop 1
	v_permlane32_swap_b32_e32 v79, v80
	v_max_f32_e32 v52, v80, v80
	v_max_f32_e32 v53, v79, v79
	v_max_f32_e32 v52, v53, v52
	v_add_f32_e32 v53, 0x7149f2ca, v52
	v_max_f32_e32 v52, 0xf149f2ca, v52
	v_cmp_ge_f32_e32 vcc, s92, v53
	v_sub_f32_e32 v53, 0xf149f2ca, v52
	v_mul_f32_e32 v53, 0x3e0293ee, v53
	v_exp_f32_e32 v53, v53
	s_cmp_eq_u64 vcc, exec
	s_cselect_b64 vcc, -1, 0
	s_waitcnt vmcnt(4)
	v_cndmask_b32_e64 v203, v53, 1.0, vcc
	v_mov_b32_e32 v53, 0xf149f2ca
	v_cndmask_b32_e32 v170, v52, v53, vcc
	v_mul_f32_e32 v52, 0xbe0293ee, v170
	v_fmamk_f32 v16, v16, 0x3e0293ee, v52
	v_exp_f32_e32 v163, v16
	v_fmamk_f32 v16, v17, 0x3e0293ee, v52
	v_exp_f32_e32 v177, v16
	v_fmamk_f32 v16, v18, 0x3e0293ee, v52
	v_exp_f32_e32 v164, v16
	v_fmamk_f32 v16, v19, 0x3e0293ee, v52
	v_exp_f32_e32 v207, v16
	v_fmamk_f32 v16, v20, 0x3e0293ee, v52
	v_exp_f32_e32 v176, v16
	v_fmamk_f32 v16, v21, 0x3e0293ee, v52
	v_exp_f32_e32 v210, v16
	v_fmamk_f32 v16, v22, 0x3e0293ee, v52
	v_exp_f32_e32 v165, v16
	v_fmamk_f32 v16, v23, 0x3e0293ee, v52
	v_exp_f32_e32 v175, v16
	v_fmamk_f32 v16, v24, 0x3e0293ee, v52
	v_exp_f32_e32 v166, v16
	v_fmamk_f32 v16, v25, 0x3e0293ee, v52
	v_exp_f32_e32 v173, v16
	v_fmamk_f32 v16, v26, 0x3e0293ee, v52
	v_exp_f32_e32 v167, v16
	v_fmamk_f32 v16, v27, 0x3e0293ee, v52
	v_exp_f32_e32 v174, v16
	v_fmamk_f32 v16, v28, 0x3e0293ee, v52
	v_exp_f32_e32 v168, v16
	v_fmamk_f32 v16, v29, 0x3e0293ee, v52
	v_exp_f32_e32 v171, v16
	v_fmamk_f32 v16, v30, 0x3e0293ee, v52
	v_pk_fma_f32 v[146:147], v[46:47], s[88:89], v[52:53] op_sel_hi:[1,0,0]
	v_pk_fma_f32 v[152:153], v[44:45], s[88:89], v[52:53] op_sel_hi:[1,0,0]
	v_pk_fma_f32 v[156:157], v[42:43], s[88:89], v[52:53] op_sel_hi:[1,0,0]
	v_pk_fma_f32 v[148:149], v[40:41], s[88:89], v[52:53] op_sel_hi:[1,0,0]
	v_pk_fma_f32 v[150:151], v[38:39], s[88:89], v[52:53] op_sel_hi:[1,0,0]
	v_pk_fma_f32 v[154:155], v[36:37], s[88:89], v[52:53] op_sel_hi:[1,0,0]
	v_pk_fma_f32 v[158:159], v[34:35], s[88:89], v[52:53] op_sel_hi:[1,0,0]
	v_pk_fma_f32 v[160:161], v[32:33], s[88:89], v[52:53] op_sel_hi:[1,0,0]
	v_exp_f32_e32 v169, v16
	v_fmac_f32_e32 v52, 0x3e0293ee, v31
	v_mov_b32_e32 v16, 0x210000
	v_exp_f32_e32 v172, v52
	v_mad_i64_i32 v[16:17], s[6:7], s26, v16, v[48:49]
	v_and_b32_e32 v18, 15, v76
	s_addk_i32 s27, 0x4000
	v_lshl_or_b32 v16, v18, 4, v16
	s_waitcnt vmcnt(7)
	ds_write_b128 v190, v[54:57] offset:16384
	s_waitcnt vmcnt(6)
	ds_write_b128 v191, v[58:61] offset:16384
	s_waitcnt vmcnt(5)
	ds_write_b128 v188, v[62:65] offset:49152
	s_waitcnt vmcnt(4)
	ds_write_b128 v189, v[66:69] offset:49152
	v_add_u32_e32 v186, s27, v51
	v_lshl_add_u64 v[178:179], s[46:47], 0, v[16:17]
	v_mov_b64_e32 v[62:63], v[14:15]
	v_mov_b64_e32 v[46:47], v[14:15]
	v_mov_b64_e32 v[30:31], v[14:15]
	v_cmp_gt_u32_e64 s[40:41], 32, v77
	v_mov_b64_e32 v[60:61], v[12:13]
	v_mov_b64_e32 v[58:59], v[10:11]
	v_mov_b64_e32 v[56:57], v[8:9]
	v_mov_b64_e32 v[54:55], v[6:7]
	v_mov_b64_e32 v[52:53], v[4:5]
	v_mov_b64_e32 v[50:51], v[2:3]
	v_mov_b64_e32 v[48:49], v[0:1]
	v_mov_b64_e32 v[44:45], v[12:13]
	v_mov_b64_e32 v[42:43], v[10:11]
	v_mov_b64_e32 v[40:41], v[8:9]
	v_mov_b64_e32 v[38:39], v[6:7]
	v_mov_b64_e32 v[36:37], v[4:5]
	v_mov_b64_e32 v[34:35], v[2:3]
	v_mov_b64_e32 v[32:33], v[0:1]
	v_mov_b64_e32 v[28:29], v[12:13]
	v_mov_b64_e32 v[26:27], v[10:11]
	v_mov_b64_e32 v[24:25], v[8:9]
	v_mov_b64_e32 v[22:23], v[6:7]
	v_mov_b64_e32 v[20:21], v[4:5]
	v_mov_b64_e32 v[18:19], v[2:3]
	v_mov_b64_e32 v[16:17], v[0:1]
	s_waitcnt lgkmcnt(0)
	s_barrier
	v_readfirstlane_b32 s66, v178
	v_readfirstlane_b32 s67, v179
	s_nop 3
	v_subrev_u32_e32 v178, s66, v178
	v_add_u32_e32 v179, 0x2000, v178
	s_add_u32 s98, s66, 0xfef7a000
	s_addc_u32 s99, s67, -1
	s_add_u32 s66, s66, 0xffffa000
	s_addc_u32 s67, s67, -1
.LBB0_526:
	ds_read_b128 v[64:67], v192 offset:49152
	ds_read_b128 v[68:71], v192 offset:57344
	ds_read_b128 v[232:235], v200 offset:49152
	ds_read_b128 v[236:239], v200 offset:57344
	ds_read_b128 v[250:253], v199 offset:49152
	ds_read_b128 v[244:247], v199 offset:57344
	ds_read_b128 v[212:215], v198 offset:49152
	ds_read_b128 v[216:219], v198 offset:57344
	v_add_f32_e32 v162, 0, v163
	v_add_f32_e32 v162, v177, v162
	s_waitcnt lgkmcnt(6)
	v_mfma_f32_32x32x16_bf16 v[80:95], v[64:67], v[118:121], 0
	v_add_f32_e32 v162, v164, v162
	v_add_f32_e32 v162, v207, v162
	v_add_f32_e32 v162, v176, v162
	v_add_f32_e32 v162, v210, v162
	v_mfma_f32_32x32x16_bf16 v[64:79], v[68:71], v[118:121], 0
	v_add_f32_e32 v162, v165, v162
	v_add_f32_e32 v162, v175, v162
	v_add_f32_e32 v162, v166, v162
	v_add_f32_e32 v162, v173, v162
	v_add_f32_e32 v162, v167, v162
	s_waitcnt lgkmcnt(4)
	v_mfma_f32_32x32x16_bf16 v[80:95], v[232:235], v[114:117], v[80:95]
	ds_read_b128 v[232:235], v195 offset:49152
	v_add_f32_e32 v162, v174, v162
	v_exp_f32_e32 v160, v160
	v_add_f32_e32 v162, v168, v162
	v_exp_f32_e32 v161, v161
	v_mfma_f32_32x32x16_bf16 v[64:79], v[236:239], v[114:117], v[64:79]
	ds_read_b128 v[236:239], v195 offset:57344
	v_add_f32_e32 v162, v171, v162
	v_exp_f32_e32 v158, v158
	v_add_f32_e32 v162, v169, v162
	v_exp_f32_e32 v159, v159
	s_waitcnt lgkmcnt(4)
	v_mfma_f32_32x32x16_bf16 v[80:95], v[250:253], v[126:129], v[80:95]
	ds_read_b128 v[250:253], v193 offset:49152
	v_add_f32_e32 v162, v172, v162
	v_exp_f32_e32 v154, v154
	v_add_f32_e32 v162, v160, v162
	v_exp_f32_e32 v155, v155
	v_mfma_f32_32x32x16_bf16 v[64:79], v[244:247], v[126:129], v[64:79]
	ds_read_b128 v[244:247], v193 offset:57344
	v_add_f32_e32 v162, v161, v162
	v_exp_f32_e32 v150, v150
	v_add_f32_e32 v162, v158, v162
	v_exp_f32_e32 v151, v151
	s_waitcnt lgkmcnt(4)
	v_mfma_f32_32x32x16_bf16 v[80:95], v[212:215], v[122:125], v[80:95]
	ds_read_b128 v[212:215], v202 offset:49152
	v_add_f32_e32 v162, v159, v162
	v_exp_f32_e32 v148, v148
	v_add_f32_e32 v162, v154, v162
	v_exp_f32_e32 v149, v149
	v_mfma_f32_32x32x16_bf16 v[64:79], v[216:219], v[122:125], v[64:79]
	ds_read_b128 v[216:219], v202 offset:57344
	v_add_f32_e32 v162, v155, v162
	v_exp_f32_e32 v156, v156
	v_add_f32_e32 v162, v150, v162
	v_exp_f32_e32 v157, v157
	s_waitcnt lgkmcnt(4)
	v_mfma_f32_32x32x16_bf16 v[80:95], v[232:235], v[110:113], v[80:95]
	ds_read_b128 v[232:235], v201 offset:49152
	v_add_f32_e32 v162, v151, v162
	v_exp_f32_e32 v152, v152
	v_add_f32_e32 v162, v148, v162
	v_exp_f32_e32 v153, v153
	v_mfma_f32_32x32x16_bf16 v[64:79], v[236:239], v[110:113], v[64:79]
	ds_read_b128 v[236:239], v201 offset:57344
	v_add_f32_e32 v162, v149, v162
	v_exp_f32_e32 v146, v146
	v_add_f32_e32 v162, v156, v162
	v_exp_f32_e32 v147, v147
	s_waitcnt lgkmcnt(4)
	v_mfma_f32_32x32x16_bf16 v[80:95], v[250:253], v[106:109], v[80:95]
	v_add_f32_e32 v162, v157, v162
	v_add_f32_e32 v162, v152, v162
	v_add_f32_e32 v162, v153, v162
	v_add_f32_e32 v162, v146, v162
	v_add_f32_e32 v204, v147, v162
	v_mov_b32_e32 v205, v204
	v_mfma_f32_32x32x16_bf16 v[64:79], v[244:247], v[106:109], v[64:79]
	v_permlane32_swap_b32_e32 v204, v205
	v_cvt_pk_bf16_f32 v162, v163, v177
	v_cvt_pk_bf16_f32 v163, v164, v207
	v_cvt_pk_bf16_f32 v164, v176, v210
	s_waitcnt lgkmcnt(2)
	v_mfma_f32_32x32x16_bf16 v[80:95], v[212:215], v[102:105], v[80:95]
	v_cvt_pk_bf16_f32 v165, v165, v175
	v_cvt_pk_bf16_f32 v166, v166, v173
	v_cvt_pk_bf16_f32 v167, v167, v174
	v_cvt_pk_bf16_f32 v168, v168, v171
	v_mfma_f32_32x32x16_bf16 v[64:79], v[216:219], v[102:105], v[64:79]
	v_cvt_pk_bf16_f32 v169, v169, v172
	v_cvt_pk_bf16_f32 v172, v160, v161
	v_cvt_pk_bf16_f32 v173, v158, v159
	v_cvt_pk_bf16_f32 v174, v154, v155
	ds_read_b64_tr_b16 v[210:211], v187 offset:0x0
	ds_read_b64_tr_b16 v[212:213], v187 offset:0x800
	ds_read_b64_tr_b16 v[214:215], v187 offset:0x200
	ds_read_b64_tr_b16 v[216:217], v187 offset:0xa00
	ds_read_b64_tr_b16 v[218:219], v187 offset:0x400
	ds_read_b64_tr_b16 v[220:221], v187 offset:0xc00
	ds_read_b64_tr_b16 v[222:223], v187 offset:0x600
	ds_read_b64_tr_b16 v[224:225], v187 offset:0xe00
	s_waitcnt lgkmcnt(8)
	v_mfma_f32_32x32x16_bf16 v[80:95], v[232:235], v[98:101], v[80:95]
	v_cvt_pk_bf16_f32 v175, v150, v151
	v_cvt_pk_bf16_f32 v206, v148, v149
	v_cvt_pk_bf16_f32 v207, v156, v157
	v_mfma_f32_32x32x16_bf16 v[64:79], v[236:239], v[98:101], v[64:79]
	v_cvt_pk_bf16_f32 v208, v152, v153
	v_cvt_pk_bf16_f32 v209, v146, v147
	s_nop 1
	v_permlane32_swap_b32_e32 v162, v164
	v_permlane32_swap_b32_e32 v206, v208
	v_permlane32_swap_b32_e32 v163, v165
	v_permlane32_swap_b32_e32 v166, v168
	v_permlane32_swap_b32_e32 v167, v169
	v_permlane32_swap_b32_e32 v172, v174
	v_permlane32_swap_b32_e32 v173, v175
	v_permlane32_swap_b32_e32 v207, v209
	s_waitcnt vmcnt(0)
	ds_write_b128 v188, v[134:137] offset:32768
	ds_write_b128 v189, v[142:145] offset:32768
	global_load_dwordx4 v[146:149], v178, s[66:67]
	global_load_dwordx4 v[150:153], v179, s[66:67]
	global_load_dwordx4 v[154:157], v178, s[98:99]
	global_load_dwordx4 v[158:161], v179, s[98:99]
	s_add_u32 s66, s66, 0x4000
	s_addc_u32 s67, s67, 0
	s_add_u32 s98, s98, 0x4000
	s_addc_u32 s99, s99, 0
	s_waitcnt lgkmcnt(6)
	v_mfma_f32_32x32x16_bf16 v[0:15], v[162:165], v[210:213], v[0:15]
	ds_read_b64_tr_b16 v[210:211], v187 offset:0x1000
	ds_read_b64_tr_b16 v[212:213], v187 offset:0x1800
	v_max_f32_e32 v240, v80, v81
	v_max3_f32 v240, v240, v82, v83
	v_max3_f32 v240, v240, v84, v85
	v_max3_f32 v240, v240, v86, v87
	v_max3_f32 v240, v240, v88, v89
	v_mfma_f32_32x32x16_bf16 v[48:63], v[162:165], v[214:217], v[48:63]
	ds_read_b64_tr_b16 v[214:215], v187 offset:0x1200
	ds_read_b64_tr_b16 v[216:217], v187 offset:0x1a00
	v_max3_f32 v240, v240, v90, v91
	v_max3_f32 v240, v240, v92, v93
	v_max3_f32 v240, v240, v94, v95
	v_max3_f32 v240, v240, v64, v65
	v_max3_f32 v240, v240, v66, v67
	v_max3_f32 v240, v240, v68, v69
	s_waitcnt lgkmcnt(6)
	v_mfma_f32_32x32x16_bf16 v[32:47], v[162:165], v[218:221], v[32:47]
	ds_read_b64_tr_b16 v[218:219], v187 offset:0x1400
	ds_read_b64_tr_b16 v[220:221], v187 offset:0x1c00
	v_max3_f32 v240, v240, v70, v71
	v_max3_f32 v240, v240, v72, v73
	v_max3_f32 v240, v240, v74, v75
	v_max3_f32 v240, v240, v76, v77
	v_max3_f32 v240, v240, v78, v79
	v_mfma_f32_32x32x16_bf16 v[16:31], v[162:165], v[222:225], v[16:31]
	ds_read_b64_tr_b16 v[222:223], v187 offset:0x1600
	ds_read_b64_tr_b16 v[224:225], v187 offset:0x1e00
	v_mov_b32_e32 v241, v240
	s_nop 1
	v_permlane32_swap_b32_e32 v240, v241
	v_max_f32_e32 v240, v240, v241
	v_sub_f32_e32 v241, v240, v170
	v_cmp_ge_f32_e32 vcc, s92, v241
	s_waitcnt lgkmcnt(4)
	v_mfma_f32_32x32x16_bf16 v[0:15], v[166:169], v[210:213], v[0:15]
	ds_read_b64_tr_b16 v[210:211], v187 offset:0x2000
	ds_read_b64_tr_b16 v[212:213], v187 offset:0x2800
	v_max_f32_e32 v240, v170, v240
	v_sub_f32_e32 v241, v170, v240
	v_mul_f32_e32 v241, 0x3e0293ee, v241
	v_exp_f32_e32 v241, v241
	s_cmp_eq_u64 vcc, exec
	s_cselect_b64 s[42:43], -1, 0
	v_mfma_f32_32x32x16_bf16 v[48:63], v[166:169], v[214:217], v[48:63]
	ds_read_b64_tr_b16 v[214:215], v187 offset:0x2200
	ds_read_b64_tr_b16 v[216:217], v187 offset:0x2a00
	v_cndmask_b32_e64 v242, v240, v170, s[42:43]
	v_mul_f32_e32 v243, 0xbe0293ee, v242
	v_fmamk_f32 v80, v80, 0x3e0293ee, v243
	v_fmamk_f32 v81, v81, 0x3e0293ee, v243
	v_fmamk_f32 v82, v82, 0x3e0293ee, v243
	v_fmamk_f32 v83, v83, 0x3e0293ee, v243
	s_waitcnt lgkmcnt(4)
	v_mfma_f32_32x32x16_bf16 v[32:47], v[166:169], v[218:221], v[32:47]
	ds_read_b64_tr_b16 v[218:219], v187 offset:0x2400
	ds_read_b64_tr_b16 v[220:221], v187 offset:0x2c00
	v_fmamk_f32 v84, v84, 0x3e0293ee, v243
	v_fmamk_f32 v85, v85, 0x3e0293ee, v243
	v_fmamk_f32 v86, v86, 0x3e0293ee, v243
	v_fmamk_f32 v87, v87, 0x3e0293ee, v243
	v_fmamk_f32 v88, v88, 0x3e0293ee, v243
	v_fmamk_f32 v89, v89, 0x3e0293ee, v243
	v_mfma_f32_32x32x16_bf16 v[16:31], v[166:169], v[222:225], v[16:31]
	ds_read_b64_tr_b16 v[222:223], v187 offset:0x2600
	ds_read_b64_tr_b16 v[224:225], v187 offset:0x2e00
	v_fmamk_f32 v90, v90, 0x3e0293ee, v243
	v_fmamk_f32 v91, v91, 0x3e0293ee, v243
	v_fmamk_f32 v92, v92, 0x3e0293ee, v243
	v_fmamk_f32 v93, v93, 0x3e0293ee, v243
	v_fmamk_f32 v94, v94, 0x3e0293ee, v243
	v_fmamk_f32 v95, v95, 0x3e0293ee, v243
	s_waitcnt lgkmcnt(4)
	v_mfma_f32_32x32x16_bf16 v[0:15], v[172:175], v[210:213], v[0:15]
	ds_read_b64_tr_b16 v[210:211], v187 offset:0x3000
	ds_read_b64_tr_b16 v[212:213], v187 offset:0x3800
	v_exp_f32_e32 v177, v81
	v_exp_f32_e32 v176, v83
	v_exp_f32_e32 v171, v93
	v_mfma_f32_32x32x16_bf16 v[48:63], v[172:175], v[214:217], v[48:63]
	ds_read_b64_tr_b16 v[214:215], v187 offset:0x3200
	ds_read_b64_tr_b16 v[216:217], v187 offset:0x3a00
	v_exp_f32_e32 v170, v95
	v_exp_f32_e32 v162, v80
	v_exp_f32_e32 v163, v82
	s_waitcnt lgkmcnt(4)
	v_mfma_f32_32x32x16_bf16 v[32:47], v[172:175], v[218:221], v[32:47]
	ds_read_b64_tr_b16 v[218:219], v187 offset:0x3400
	ds_read_b64_tr_b16 v[220:221], v187 offset:0x3c00
	v_exp_f32_e32 v164, v84
	v_exp_f32_e32 v165, v86
	v_exp_f32_e32 v166, v88
	v_mfma_f32_32x32x16_bf16 v[16:31], v[172:175], v[222:225], v[16:31]
	ds_read_b64_tr_b16 v[222:223], v187 offset:0x3600
	ds_read_b64_tr_b16 v[224:225], v187 offset:0x3e00
	v_exp_f32_e32 v167, v90
	v_exp_f32_e32 v168, v92
	v_exp_f32_e32 v169, v94
	s_waitcnt lgkmcnt(4)
	v_mfma_f32_32x32x16_bf16 v[0:15], v[206:209], v[210:213], v[0:15]
	v_exp_f32_e32 v175, v85
	v_exp_f32_e32 v174, v87
	v_exp_f32_e32 v173, v89
	v_mfma_f32_32x32x16_bf16 v[48:63], v[206:209], v[214:217], v[48:63]
	v_exp_f32_e32 v172, v91
	s_waitcnt lgkmcnt(0)
	v_mfma_f32_32x32x16_bf16 v[32:47], v[206:209], v[218:221], v[32:47]
	v_mfma_f32_32x32x16_bf16 v[16:31], v[206:209], v[222:225], v[16:31]
	s_barrier
	v_cndmask_b32_e64 v206, v241, 1.0, s[42:43]
	v_cmp_gt_f32_e32 vcc, 1.0, v206
	ds_write_b128 v190, v[130:133]
	ds_write_b128 v191, v[138:141]
	s_cbranch_vccz .LBB0_530
	s_and_saveexec_b64 s[6:7], s[40:41]
	ds_write_b32 v184, v206 offset:128
	s_or_b64 exec, exec, s[6:7]
	s_waitcnt lgkmcnt(0)
	ds_read_b128 v[210:213], v182 offset:224
	ds_read_b128 v[214:217], v182 offset:192
	ds_read_b128 v[218:221], v182 offset:160
	ds_read_b128 v[222:225], v182 offset:128
	s_waitcnt lgkmcnt(3)
	v_pk_mul_f32 v[14:15], v[14:15], v[212:213]
	s_waitcnt lgkmcnt(2)
	v_pk_mul_f32 v[10:11], v[10:11], v[216:217]
	s_waitcnt lgkmcnt(1)
	v_pk_mul_f32 v[6:7], v[6:7], v[220:221]
	s_waitcnt lgkmcnt(0)
	v_pk_mul_f32 v[2:3], v[2:3], v[224:225]
	v_pk_mul_f32 v[12:13], v[12:13], v[210:211]
	v_pk_mul_f32 v[8:9], v[8:9], v[214:215]
	v_pk_mul_f32 v[4:5], v[4:5], v[218:219]
	v_pk_mul_f32 v[0:1], v[0:1], v[222:223]
	v_pk_mul_f32 v[62:63], v[62:63], v[212:213]
	v_pk_mul_f32 v[58:59], v[58:59], v[216:217]
	v_pk_mul_f32 v[54:55], v[54:55], v[220:221]
	v_pk_mul_f32 v[50:51], v[50:51], v[224:225]
	v_pk_mul_f32 v[60:61], v[60:61], v[210:211]
	v_pk_mul_f32 v[56:57], v[56:57], v[214:215]
	v_pk_mul_f32 v[52:53], v[52:53], v[218:219]
	v_pk_mul_f32 v[48:49], v[48:49], v[222:223]
	v_pk_mul_f32 v[46:47], v[46:47], v[212:213]
	v_pk_mul_f32 v[42:43], v[42:43], v[216:217]
	v_pk_mul_f32 v[38:39], v[38:39], v[220:221]
	v_pk_mul_f32 v[34:35], v[34:35], v[224:225]
	v_pk_mul_f32 v[44:45], v[44:45], v[210:211]
	v_pk_mul_f32 v[40:41], v[40:41], v[214:215]
	v_pk_mul_f32 v[36:37], v[36:37], v[218:219]
	v_pk_mul_f32 v[32:33], v[32:33], v[222:223]
	v_pk_mul_f32 v[30:31], v[30:31], v[212:213]
	v_pk_mul_f32 v[26:27], v[26:27], v[216:217]
	v_pk_mul_f32 v[22:23], v[22:23], v[220:221]
	v_pk_mul_f32 v[18:19], v[18:19], v[224:225]
	v_pk_mul_f32 v[28:29], v[28:29], v[210:211]
	v_pk_mul_f32 v[24:25], v[24:25], v[214:215]
	v_pk_mul_f32 v[20:21], v[20:21], v[218:219]
	v_pk_mul_f32 v[16:17], v[16:17], v[222:223]
.LBB0_530:
	v_fmamk_f32 v217, v64, 0x3e0293ee, v243
	v_fmamk_f32 v218, v65, 0x3e0293ee, v243
	v_fmamk_f32 v219, v66, 0x3e0293ee, v243
	v_fmamk_f32 v220, v67, 0x3e0293ee, v243
	v_fmamk_f32 v221, v68, 0x3e0293ee, v243
	v_fmamk_f32 v210, v69, 0x3e0293ee, v243
	v_fmamk_f32 v211, v70, 0x3e0293ee, v243
	v_fmamk_f32 v212, v71, 0x3e0293ee, v243
	v_fmamk_f32 v213, v72, 0x3e0293ee, v243
	v_fmamk_f32 v214, v73, 0x3e0293ee, v243
	v_fmamk_f32 v215, v74, 0x3e0293ee, v243
	v_fmamk_f32 v216, v75, 0x3e0293ee, v243
	v_fmamk_f32 v209, v76, 0x3e0293ee, v243
	v_fmamk_f32 v222, v77, 0x3e0293ee, v243
	v_fmamk_f32 v223, v78, 0x3e0293ee, v243
	v_fmamk_f32 v208, v79, 0x3e0293ee, v243
	s_waitcnt lgkmcnt(0)
	s_barrier
	ds_read_b128 v[64:67], v192 offset:32768
	ds_read_b128 v[68:71], v192 offset:40960
	ds_read_b128 v[232:235], v200 offset:32768
	ds_read_b128 v[236:239], v200 offset:40960
	ds_read_b128 v[250:253], v199 offset:32768
	ds_read_b128 v[244:247], v199 offset:40960
	ds_read_b128 v[224:227], v198 offset:32768
	ds_read_b128 v[228:231], v198 offset:40960
	v_exp_f32_e32 v248, v208
	v_exp_f32_e32 v249, v209
	s_waitcnt lgkmcnt(6)
	v_mfma_f32_32x32x16_bf16 v[80:95], v[64:67], v[118:121], 0
	v_exp_f32_e32 v217, v217
	v_add_f32_e32 v208, 0, v162
	v_add_f32_e32 v208, v177, v208
	v_exp_f32_e32 v218, v218
	v_mfma_f32_32x32x16_bf16 v[64:79], v[68:71], v[118:121], 0
	v_add_f32_e32 v208, v163, v208
	v_exp_f32_e32 v219, v219
	v_add_f32_e32 v208, v176, v208
	v_exp_f32_e32 v220, v220
	v_add_f32_e32 v208, v164, v208
	s_waitcnt lgkmcnt(4)
	v_mfma_f32_32x32x16_bf16 v[80:95], v[232:235], v[114:117], v[80:95]
	ds_read_b128 v[232:235], v195 offset:32768
	v_exp_f32_e32 v221, v221
	v_add_f32_e32 v208, v175, v208
	v_exp_f32_e32 v210, v210
	v_add_f32_e32 v208, v165, v208
	v_mfma_f32_32x32x16_bf16 v[64:79], v[236:239], v[114:117], v[64:79]
	ds_read_b128 v[236:239], v195 offset:40960
	v_exp_f32_e32 v211, v211
	v_add_f32_e32 v208, v174, v208
	v_exp_f32_e32 v212, v212
	v_add_f32_e32 v208, v166, v208
	s_waitcnt lgkmcnt(4)
	v_mfma_f32_32x32x16_bf16 v[80:95], v[250:253], v[126:129], v[80:95]
	ds_read_b128 v[250:253], v193 offset:32768
	v_exp_f32_e32 v213, v213
	v_add_f32_e32 v208, v173, v208
	v_exp_f32_e32 v214, v214
	v_add_f32_e32 v208, v167, v208
	v_mfma_f32_32x32x16_bf16 v[64:79], v[244:247], v[126:129], v[64:79]
	ds_read_b128 v[244:247], v193 offset:40960
	v_exp_f32_e32 v215, v215
	v_add_f32_e32 v208, v172, v208
	v_exp_f32_e32 v216, v216
	v_add_f32_e32 v208, v168, v208
	s_waitcnt lgkmcnt(4)
	v_mfma_f32_32x32x16_bf16 v[80:95], v[224:227], v[122:125], v[80:95]
	ds_read_b128 v[224:227], v202 offset:32768
	v_exp_f32_e32 v222, v222
	v_add_f32_e32 v208, v171, v208
	v_exp_f32_e32 v223, v223
	v_add_f32_e32 v208, v169, v208
	v_mfma_f32_32x32x16_bf16 v[64:79], v[228:231], v[122:125], v[64:79]
	ds_read_b128 v[228:231], v202 offset:40960
	v_add_f32_e32 v208, v170, v208
	v_add_f32_e32 v208, v217, v208
	v_add_f32_e32 v208, v218, v208
	v_add_f32_e32 v208, v219, v208
	s_waitcnt lgkmcnt(4)
	v_mfma_f32_32x32x16_bf16 v[80:95], v[232:235], v[110:113], v[80:95]
	ds_read_b128 v[232:235], v201 offset:32768
	v_add_f32_e32 v208, v220, v208
	v_add_f32_e32 v208, v221, v208
	v_add_f32_e32 v208, v210, v208
	v_add_f32_e32 v208, v211, v208
	v_mfma_f32_32x32x16_bf16 v[64:79], v[236:239], v[110:113], v[64:79]
	ds_read_b128 v[236:239], v201 offset:40960
	v_add_f32_e32 v208, v212, v208
	v_add_f32_e32 v208, v213, v208
	v_add_f32_e32 v208, v214, v208
	v_add_f32_e32 v208, v215, v208
	s_waitcnt lgkmcnt(4)
	v_mfma_f32_32x32x16_bf16 v[80:95], v[250:253], v[106:109], v[80:95]
	v_add_f32_e32 v208, v216, v208
	v_add_f32_e32 v208, v249, v208
	v_add_f32_e32 v208, v222, v208
	v_add_f32_e32 v208, v223, v208
	v_mfma_f32_32x32x16_bf16 v[64:79], v[244:247], v[106:109], v[64:79]
	v_add_f32_e32 v208, v248, v208
	v_mov_b32_e32 v209, v208
	v_cvt_pk_bf16_f32 v162, v162, v177
	v_cvt_pk_bf16_f32 v163, v163, v176
	s_waitcnt lgkmcnt(2)
	v_mfma_f32_32x32x16_bf16 v[80:95], v[224:227], v[102:105], v[80:95]
	v_cvt_pk_bf16_f32 v164, v164, v175
	v_cvt_pk_bf16_f32 v165, v165, v174
	v_cvt_pk_bf16_f32 v166, v166, v173
	v_cvt_pk_bf16_f32 v167, v167, v172
	v_mfma_f32_32x32x16_bf16 v[64:79], v[228:231], v[102:105], v[64:79]
	v_cvt_pk_bf16_f32 v168, v168, v171
	v_cvt_pk_bf16_f32 v169, v169, v170
	v_cvt_pk_bf16_f32 v170, v217, v218
	v_cvt_pk_bf16_f32 v171, v219, v220
	s_waitcnt lgkmcnt(0)
	v_mfma_f32_32x32x16_bf16 v[80:95], v[232:235], v[98:101], v[80:95]
	v_cvt_pk_bf16_f32 v172, v221, v210
	v_cvt_pk_bf16_f32 v173, v211, v212
	v_cvt_pk_bf16_f32 v174, v213, v214
	v_cvt_pk_bf16_f32 v175, v215, v216
	v_mfma_f32_32x32x16_bf16 v[64:79], v[236:239], v[98:101], v[64:79]
	v_cvt_pk_bf16_f32 v176, v249, v222
	v_cvt_pk_bf16_f32 v177, v223, v248
	ds_read_b64_tr_b16 v[210:211], v186 offset:0x0
	ds_read_b64_tr_b16 v[212:213], v186 offset:0x800
	ds_read_b64_tr_b16 v[214:215], v186 offset:0x200
	ds_read_b64_tr_b16 v[216:217], v186 offset:0xa00
	ds_read_b64_tr_b16 v[218:219], v186 offset:0x400
	ds_read_b64_tr_b16 v[220:221], v186 offset:0xc00
	ds_read_b64_tr_b16 v[222:223], v186 offset:0x600
	ds_read_b64_tr_b16 v[224:225], v186 offset:0xe00
	s_nop 1
	v_permlane32_swap_b32_e32 v208, v209
	v_permlane32_swap_b32_e32 v162, v164
	v_permlane32_swap_b32_e32 v163, v165
	v_permlane32_swap_b32_e32 v166, v168
	v_permlane32_swap_b32_e32 v167, v169
	v_permlane32_swap_b32_e32 v170, v172
	v_permlane32_swap_b32_e32 v171, v173
	v_permlane32_swap_b32_e32 v174, v176
	v_permlane32_swap_b32_e32 v175, v177
	s_waitcnt vmcnt(1)
	ds_write_b128 v188, v[154:157] offset:49152
	s_waitcnt vmcnt(0)
	ds_write_b128 v189, v[158:161] offset:49152
	s_cmp_ge_u32 s34, s35
	s_cselect_b64 s[6:7], -1, 0
	s_cbranch_scc1 .LBB0_532
	global_load_dwordx4 v[130:133], v178, s[66:67]
	global_load_dwordx4 v[134:137], v178, s[98:99]
	global_load_dwordx4 v[138:141], v179, s[66:67]
	global_load_dwordx4 v[142:145], v179, s[98:99]
	s_add_u32 s66, s66, 0x4000
	s_addc_u32 s67, s67, 0
	s_add_u32 s98, s98, 0x4000
	s_addc_u32 s99, s99, 0
.LBB0_532:
	s_waitcnt lgkmcnt(6)
	v_mfma_f32_32x32x16_bf16 v[0:15], v[162:165], v[210:213], v[0:15]
	ds_read_b64_tr_b16 v[210:211], v186 offset:0x1000
	ds_read_b64_tr_b16 v[212:213], v186 offset:0x1800
	v_max_f32_e32 v240, v80, v81
	v_max3_f32 v240, v240, v82, v83
	v_max3_f32 v240, v240, v84, v85
	v_max3_f32 v240, v240, v86, v87
	v_max3_f32 v240, v240, v88, v89
	v_mfma_f32_32x32x16_bf16 v[48:63], v[162:165], v[214:217], v[48:63]
	ds_read_b64_tr_b16 v[214:215], v186 offset:0x1200
	ds_read_b64_tr_b16 v[216:217], v186 offset:0x1a00
	v_max3_f32 v240, v240, v90, v91
	v_max3_f32 v240, v240, v92, v93
	v_max3_f32 v240, v240, v94, v95
	v_max3_f32 v240, v240, v64, v65
	v_max3_f32 v240, v240, v66, v67
	v_max3_f32 v240, v240, v68, v69
	s_waitcnt lgkmcnt(6)
	v_mfma_f32_32x32x16_bf16 v[32:47], v[162:165], v[218:221], v[32:47]
	ds_read_b64_tr_b16 v[218:219], v186 offset:0x1400
	ds_read_b64_tr_b16 v[220:221], v186 offset:0x1c00
	v_max3_f32 v240, v240, v70, v71
	v_max3_f32 v240, v240, v72, v73
	v_max3_f32 v240, v240, v74, v75
	v_max3_f32 v240, v240, v76, v77
	v_max3_f32 v240, v240, v78, v79
	v_mfma_f32_32x32x16_bf16 v[16:31], v[162:165], v[222:225], v[16:31]
	ds_read_b64_tr_b16 v[222:223], v186 offset:0x1600
	ds_read_b64_tr_b16 v[224:225], v186 offset:0x1e00
	v_mov_b32_e32 v241, v240
	s_nop 1
	v_permlane32_swap_b32_e32 v240, v241
	v_max_f32_e32 v240, v240, v241
	v_sub_f32_e32 v241, v240, v242
	v_cmp_ge_f32_e32 vcc, s92, v241
	s_waitcnt lgkmcnt(4)
	v_mfma_f32_32x32x16_bf16 v[0:15], v[166:169], v[210:213], v[0:15]
	ds_read_b64_tr_b16 v[210:211], v186 offset:0x2000
	ds_read_b64_tr_b16 v[212:213], v186 offset:0x2800
	v_max_f32_e32 v241, v242, v240
	v_sub_f32_e32 v240, v242, v241
	v_mul_f32_e32 v240, 0x3e0293ee, v240
	v_exp_f32_e32 v240, v240
	s_cmp_eq_u64 vcc, exec
	s_cselect_b64 s[42:43], -1, 0
	v_mfma_f32_32x32x16_bf16 v[48:63], v[166:169], v[214:217], v[48:63]
	ds_read_b64_tr_b16 v[214:215], v186 offset:0x2200
	ds_read_b64_tr_b16 v[216:217], v186 offset:0x2a00
	v_cndmask_b32_e64 v248, v241, v242, s[42:43]
	v_mul_f32_e32 v249, 0xbe0293ee, v248
	v_fmamk_f32 v80, v80, 0x3e0293ee, v249
	v_fmamk_f32 v81, v81, 0x3e0293ee, v249
	v_fmamk_f32 v82, v82, 0x3e0293ee, v249
	v_fmamk_f32 v83, v83, 0x3e0293ee, v249
	s_waitcnt lgkmcnt(4)
	v_mfma_f32_32x32x16_bf16 v[32:47], v[166:169], v[218:221], v[32:47]
	ds_read_b64_tr_b16 v[218:219], v186 offset:0x2400
	ds_read_b64_tr_b16 v[220:221], v186 offset:0x2c00
	v_fmamk_f32 v84, v84, 0x3e0293ee, v249
	v_fmamk_f32 v85, v85, 0x3e0293ee, v249
	v_fmamk_f32 v86, v86, 0x3e0293ee, v249
	v_fmamk_f32 v87, v87, 0x3e0293ee, v249
	v_fmamk_f32 v88, v88, 0x3e0293ee, v249
	v_fmamk_f32 v89, v89, 0x3e0293ee, v249
	v_mfma_f32_32x32x16_bf16 v[16:31], v[166:169], v[222:225], v[16:31]
	ds_read_b64_tr_b16 v[222:223], v186 offset:0x2600
	ds_read_b64_tr_b16 v[224:225], v186 offset:0x2e00
	v_fmamk_f32 v90, v90, 0x3e0293ee, v249
	v_fmamk_f32 v91, v91, 0x3e0293ee, v249
	v_fmamk_f32 v92, v92, 0x3e0293ee, v249
	v_fmamk_f32 v93, v93, 0x3e0293ee, v249
	v_fmamk_f32 v94, v94, 0x3e0293ee, v249
	v_fmamk_f32 v95, v95, 0x3e0293ee, v249
	s_waitcnt lgkmcnt(4)
	v_mfma_f32_32x32x16_bf16 v[0:15], v[170:173], v[210:213], v[0:15]
	ds_read_b64_tr_b16 v[210:211], v186 offset:0x3000
	ds_read_b64_tr_b16 v[212:213], v186 offset:0x3800
	v_exp_f32_e32 v207, v83
	v_exp_f32_e32 v163, v80
	v_exp_f32_e32 v164, v82
	v_mfma_f32_32x32x16_bf16 v[48:63], v[170:173], v[214:217], v[48:63]
	ds_read_b64_tr_b16 v[214:215], v186 offset:0x3200
	ds_read_b64_tr_b16 v[216:217], v186 offset:0x3a00
	v_exp_f32_e32 v165, v86
	v_exp_f32_e32 v166, v88
	v_exp_f32_e32 v167, v90
	s_waitcnt lgkmcnt(4)
	v_mfma_f32_32x32x16_bf16 v[32:47], v[170:173], v[218:221], v[32:47]
	ds_read_b64_tr_b16 v[218:219], v186 offset:0x3400
	ds_read_b64_tr_b16 v[220:221], v186 offset:0x3c00
	v_exp_f32_e32 v168, v92
	v_exp_f32_e32 v169, v94
	v_mfma_f32_32x32x16_bf16 v[16:31], v[170:173], v[222:225], v[16:31]
	ds_read_b64_tr_b16 v[222:223], v186 offset:0x3600
	ds_read_b64_tr_b16 v[224:225], v186 offset:0x3e00
	s_waitcnt lgkmcnt(4)
	v_mfma_f32_32x32x16_bf16 v[0:15], v[174:177], v[210:213], v[0:15]
	v_exp_f32_e32 v171, v93
	v_exp_f32_e32 v172, v95
	v_exp_f32_e32 v173, v89
	v_mfma_f32_32x32x16_bf16 v[48:63], v[174:177], v[214:217], v[48:63]
	v_exp_f32_e32 v210, v85
	s_waitcnt lgkmcnt(0)
	v_mfma_f32_32x32x16_bf16 v[32:47], v[174:177], v[218:221], v[32:47]
	v_mfma_f32_32x32x16_bf16 v[16:31], v[174:177], v[222:225], v[16:31]
	v_exp_f32_e32 v174, v91
	v_exp_f32_e32 v175, v87
	v_exp_f32_e32 v176, v84
	v_exp_f32_e32 v177, v81
	s_barrier
	v_cndmask_b32_e64 v162, v240, 1.0, s[42:43]
	v_cmp_gt_f32_e32 vcc, 1.0, v162
	ds_write_b128 v190, v[146:149] offset:16384
	ds_write_b128 v191, v[150:153] offset:16384
	s_cbranch_vccz .LBB0_536
	s_and_saveexec_b64 s[8:9], s[40:41]
	ds_write_b32 v184, v162 offset:128
	s_or_b64 exec, exec, s[8:9]
	s_waitcnt lgkmcnt(0)
	ds_read_b128 v[146:149], v182 offset:224
	ds_read_b128 v[150:153], v182 offset:192
	ds_read_b128 v[154:157], v182 offset:160
	ds_read_b128 v[158:161], v182 offset:128
	s_waitcnt lgkmcnt(3)
	v_pk_mul_f32 v[14:15], v[14:15], v[148:149]
	s_waitcnt lgkmcnt(2)
	v_pk_mul_f32 v[10:11], v[10:11], v[152:153]
	s_waitcnt lgkmcnt(1)
	v_pk_mul_f32 v[6:7], v[6:7], v[156:157]
	s_waitcnt lgkmcnt(0)
	v_pk_mul_f32 v[2:3], v[2:3], v[160:161]
	v_pk_mul_f32 v[12:13], v[12:13], v[146:147]
	v_pk_mul_f32 v[8:9], v[8:9], v[150:151]
	v_pk_mul_f32 v[4:5], v[4:5], v[154:155]
	v_pk_mul_f32 v[0:1], v[0:1], v[158:159]
	v_pk_mul_f32 v[62:63], v[62:63], v[148:149]
	v_pk_mul_f32 v[58:59], v[58:59], v[152:153]
	v_pk_mul_f32 v[54:55], v[54:55], v[156:157]
	v_pk_mul_f32 v[50:51], v[50:51], v[160:161]
	v_pk_mul_f32 v[60:61], v[60:61], v[146:147]
	v_pk_mul_f32 v[56:57], v[56:57], v[150:151]
	v_pk_mul_f32 v[52:53], v[52:53], v[154:155]
	v_pk_mul_f32 v[48:49], v[48:49], v[158:159]
	v_pk_mul_f32 v[46:47], v[46:47], v[148:149]
	v_pk_mul_f32 v[42:43], v[42:43], v[152:153]
	v_pk_mul_f32 v[38:39], v[38:39], v[156:157]
	v_pk_mul_f32 v[34:35], v[34:35], v[160:161]
	v_pk_mul_f32 v[44:45], v[44:45], v[146:147]
	v_pk_mul_f32 v[40:41], v[40:41], v[150:151]
	v_pk_mul_f32 v[36:37], v[36:37], v[154:155]
	v_pk_mul_f32 v[32:33], v[32:33], v[158:159]
	v_pk_mul_f32 v[30:31], v[30:31], v[148:149]
	v_pk_mul_f32 v[26:27], v[26:27], v[152:153]
	v_pk_mul_f32 v[22:23], v[22:23], v[156:157]
	v_pk_mul_f32 v[18:19], v[18:19], v[160:161]
	v_pk_mul_f32 v[28:29], v[28:29], v[146:147]
	v_pk_mul_f32 v[24:25], v[24:25], v[150:151]
	v_pk_mul_f32 v[20:21], v[20:21], v[154:155]
	v_pk_mul_f32 v[16:17], v[16:17], v[158:159]
.LBB0_536:
	v_mov_b32_e32 v170, v248
	v_mov_b32_e32 v146, v249
	v_pk_fma_f32 v[160:161], v[64:65], s[88:89], v[146:147] op_sel_hi:[1,0,0]
	v_add_f32_e32 v64, v204, v205
	v_fmac_f32_e32 v64, v203, v185
	v_add_f32_e32 v185, v208, v209
	v_pk_fma_f32 v[158:159], v[66:67], s[88:89], v[146:147] op_sel_hi:[1,0,0]
	v_pk_fma_f32 v[154:155], v[68:69], s[88:89], v[146:147] op_sel_hi:[1,0,0]
	v_pk_fma_f32 v[150:151], v[70:71], s[88:89], v[146:147] op_sel_hi:[1,0,0]
	v_pk_fma_f32 v[148:149], v[72:73], s[88:89], v[146:147] op_sel_hi:[1,0,0]
	v_pk_fma_f32 v[156:157], v[74:75], s[88:89], v[146:147] op_sel_hi:[1,0,0]
	v_pk_fma_f32 v[152:153], v[76:77], s[88:89], v[146:147] op_sel_hi:[1,0,0]
	v_pk_fma_f32 v[146:147], v[78:79], s[88:89], v[146:147] op_sel_hi:[1,0,0]
	v_fmac_f32_e32 v185, v64, v206
	s_add_i32 s34, s34, 2
	s_and_b64 vcc, exec, s[6:7]
	s_waitcnt lgkmcnt(0)
	s_barrier
	s_cbranch_vccnz .LBB0_538
	v_mov_b32_e32 v203, v162
	s_branch .LBB0_526
